# first phase-2 ticket requested by thread 0 before the preceding grid barrier (avoids the 256-way contended first dequeue)
# baseline (speedup 1.0000x reference)
.LBB0_210:
	s_mov_b32 s99, 0
	s_cmp_lt_i32 s94, 3
	s_cselect_b64 s[24:25], -1, 0
	s_cmp_gt_i32 s95, 2
	s_cselect_b64 s[0:1], -1, 0
	s_and_b64 s[0:1], s[24:25], s[0:1]
	s_andn2_b64 vcc, exec, s[0:1]
	s_mov_b32 s0, s66
	v_writelane_b32 v196, s0, 22
	s_nop 1
	v_writelane_b32 v196, s1, 23
	v_writelane_b32 v196, s96, 24
	s_nop 1
	v_writelane_b32 v196, s97, 25
	s_cbranch_vccnz .LBB0_392
	s_andn2_b64 vcc, exec, s[4:5]
	s_cbranch_vccnz .LBB0_265
	s_mov_b64 s[0:1], exec
	v_readlane_b32 s2, v197, 0
	v_readlane_b32 s3, v197, 1
	s_and_b64 s[2:3], s[0:1], s[2:3]
	s_mov_b64 exec, s[2:3]
	s_cbranch_execz .Ldq_skip_first
	v_mov_b32_e32 v251, 0
	v_mov_b32_e32 v252, 1
	global_atomic_add v250, v251, v252, s[92:93] offset:8 sc0
.Ldq_skip_first:
	s_mov_b64 exec, s[0:1]
	s_mov_b32 s99, 1
	s_waitcnt vmcnt(0)
	s_barrier
	s_mov_b64 s[0:1], exec
	v_readlane_b32 s2, v197, 0
	v_readlane_b32 s3, v197, 1
	s_and_b64 s[2:3], s[0:1], s[2:3]
	s_mov_b64 exec, s[2:3]
	s_cbranch_execz .LBB0_264
	s_add_i32 s2, 0, 0x24010
	v_mov_b32_e32 v1, s2
	s_waitcnt vmcnt(0) expcnt(0) lgkmcnt(0)
	ds_read_b32 v3, v1
	s_add_i32 s2, 0, 0x24014
	v_mov_b32_e32 v1, s2
	ds_read_b32 v1, v1
	s_waitcnt lgkmcnt(1)
	v_cmp_ne_u32_e32 vcc, 0, v3
	s_cbranch_vccnz .LBB0_228
	v_readlane_b32 s2, v196, 3
	v_readlane_b32 s3, v196, 4
	s_load_dwordx2 s[6:7], s[2:3], 0x4
	s_add_u32 s2, s92, 0x1000
	s_addc_u32 s3, s93, 0
	s_add_u32 s4, s92, 0x1100
	s_addc_u32 s5, s93, 0
	s_waitcnt lgkmcnt(0)
	s_mul_i32 s16, s6, s66
	s_add_u32 s6, s92, 0x1200
	s_mul_i32 s16, s16, s7
	s_addc_u32 s7, s93, 0
	s_add_u32 s8, s92, 0x1300
	s_addc_u32 s9, s93, 0
	s_mov_b32 s17, 1
	v_mov_b32_e32 v17, 0
	s_branch .LBB0_216
